# V pass final rmsnorm row sums by DPP instead of ds_bpermute rounds, on top of the previous version
# speedup vs baseline: 1.0024x; 1.0002x over previous
.Lvd_cons7_Lvq_kA:
	v_cvt_pk_f32_fp8_e32 v[224:225], v96
	v_cvt_pk_f32_fp8_sdwa v[226:227], v96 src0_sel:WORD_1
	v_cvt_pk_f32_fp8_e32 v[228:229], v97
	v_cvt_pk_f32_fp8_sdwa v[230:231], v97 src0_sel:WORD_1
	v_cvt_pk_f32_fp8_e32 v[232:233], v98
	v_cvt_pk_f32_fp8_sdwa v[234:235], v98 src0_sel:WORD_1
	v_cvt_pk_f32_fp8_e32 v[236:237], v99
	v_cvt_pk_f32_fp8_sdwa v[238:239], v99 src0_sel:WORD_1
	v_pk_fma_f32 v[48:49], v[224:225], s[16:17], v[48:49] op_sel_hi:[1,0,1]
	v_pk_fma_f32 v[50:51], v[226:227], s[16:17], v[50:51] op_sel_hi:[1,0,1]
	v_pk_fma_f32 v[52:53], v[228:229], s[16:17], v[52:53] op_sel_hi:[1,0,1]
	v_pk_fma_f32 v[54:55], v[230:231], s[16:17], v[54:55] op_sel_hi:[1,0,1]
	v_pk_fma_f32 v[56:57], v[232:233], s[16:17], v[56:57] op_sel_hi:[1,0,1]
	v_pk_fma_f32 v[58:59], v[234:235], s[16:17], v[58:59] op_sel_hi:[1,0,1]
	v_pk_fma_f32 v[60:61], v[236:237], s[16:17], v[60:61] op_sel_hi:[1,0,1]
	v_pk_fma_f32 v[62:63], v[238:239], s[16:17], v[62:63] op_sel_hi:[1,0,1]
	v_cvt_pk_f32_fp8_e32 v[224:225], v100
	v_cvt_pk_f32_fp8_sdwa v[226:227], v100 src0_sel:WORD_1
	v_cvt_pk_f32_fp8_e32 v[228:229], v101
	v_cvt_pk_f32_fp8_sdwa v[230:231], v101 src0_sel:WORD_1
	v_cvt_pk_f32_fp8_e32 v[232:233], v102
	v_cvt_pk_f32_fp8_sdwa v[234:235], v102 src0_sel:WORD_1
	v_cvt_pk_f32_fp8_e32 v[236:237], v103
	v_cvt_pk_f32_fp8_sdwa v[238:239], v103 src0_sel:WORD_1
	v_pk_fma_f32 v[48:49], v[224:225], s[18:19], v[48:49] op_sel_hi:[1,0,1]
	v_pk_fma_f32 v[50:51], v[226:227], s[18:19], v[50:51] op_sel_hi:[1,0,1]
	v_pk_fma_f32 v[52:53], v[228:229], s[18:19], v[52:53] op_sel_hi:[1,0,1]
	v_pk_fma_f32 v[54:55], v[230:231], s[18:19], v[54:55] op_sel_hi:[1,0,1]
	v_pk_fma_f32 v[56:57], v[232:233], s[18:19], v[56:57] op_sel_hi:[1,0,1]
	v_pk_fma_f32 v[58:59], v[234:235], s[18:19], v[58:59] op_sel_hi:[1,0,1]
	v_pk_fma_f32 v[60:61], v[236:237], s[18:19], v[60:61] op_sel_hi:[1,0,1]
	v_pk_fma_f32 v[62:63], v[238:239], s[18:19], v[62:63] op_sel_hi:[1,0,1]
	v_cvt_pk_f32_fp8_e32 v[224:225], v104
	v_cvt_pk_f32_fp8_sdwa v[226:227], v104 src0_sel:WORD_1
	v_cvt_pk_f32_fp8_e32 v[228:229], v105
	v_cvt_pk_f32_fp8_sdwa v[230:231], v105 src0_sel:WORD_1
	v_cvt_pk_f32_fp8_e32 v[232:233], v106
	v_cvt_pk_f32_fp8_sdwa v[234:235], v106 src0_sel:WORD_1
	v_cvt_pk_f32_fp8_e32 v[236:237], v107
	v_cvt_pk_f32_fp8_sdwa v[238:239], v107 src0_sel:WORD_1
	v_pk_fma_f32 v[48:49], v[224:225], s[20:21], v[48:49] op_sel_hi:[1,0,1]
	v_pk_fma_f32 v[50:51], v[226:227], s[20:21], v[50:51] op_sel_hi:[1,0,1]
	v_pk_fma_f32 v[52:53], v[228:229], s[20:21], v[52:53] op_sel_hi:[1,0,1]
	v_pk_fma_f32 v[54:55], v[230:231], s[20:21], v[54:55] op_sel_hi:[1,0,1]
	v_pk_fma_f32 v[56:57], v[232:233], s[20:21], v[56:57] op_sel_hi:[1,0,1]
	v_pk_fma_f32 v[58:59], v[234:235], s[20:21], v[58:59] op_sel_hi:[1,0,1]
	v_pk_fma_f32 v[60:61], v[236:237], s[20:21], v[60:61] op_sel_hi:[1,0,1]
	v_pk_fma_f32 v[62:63], v[238:239], s[20:21], v[62:63] op_sel_hi:[1,0,1]
	v_cvt_pk_f32_fp8_e32 v[224:225], v108
	v_cvt_pk_f32_fp8_sdwa v[226:227], v108 src0_sel:WORD_1
	v_cvt_pk_f32_fp8_e32 v[228:229], v109
	v_cvt_pk_f32_fp8_sdwa v[230:231], v109 src0_sel:WORD_1
	v_cvt_pk_f32_fp8_e32 v[232:233], v110
	v_cvt_pk_f32_fp8_sdwa v[234:235], v110 src0_sel:WORD_1
	v_cvt_pk_f32_fp8_e32 v[236:237], v111
	v_cvt_pk_f32_fp8_sdwa v[238:239], v111 src0_sel:WORD_1
	v_pk_fma_f32 v[48:49], v[224:225], s[22:23], v[48:49] op_sel_hi:[1,0,1]
	v_pk_fma_f32 v[50:51], v[226:227], s[22:23], v[50:51] op_sel_hi:[1,0,1]
	v_pk_fma_f32 v[52:53], v[228:229], s[22:23], v[52:53] op_sel_hi:[1,0,1]
	v_pk_fma_f32 v[54:55], v[230:231], s[22:23], v[54:55] op_sel_hi:[1,0,1]
	v_pk_fma_f32 v[56:57], v[232:233], s[22:23], v[56:57] op_sel_hi:[1,0,1]
	v_pk_fma_f32 v[58:59], v[234:235], s[22:23], v[58:59] op_sel_hi:[1,0,1]
	v_pk_fma_f32 v[60:61], v[236:237], s[22:23], v[60:61] op_sel_hi:[1,0,1]
	v_pk_fma_f32 v[62:63], v[238:239], s[22:23], v[62:63] op_sel_hi:[1,0,1]
	v_cvt_pk_f32_fp8_e32 v[224:225], v112
	v_cvt_pk_f32_fp8_sdwa v[226:227], v112 src0_sel:WORD_1
	v_cvt_pk_f32_fp8_e32 v[228:229], v113
	v_cvt_pk_f32_fp8_sdwa v[230:231], v113 src0_sel:WORD_1
	v_cvt_pk_f32_fp8_e32 v[232:233], v114
	v_cvt_pk_f32_fp8_sdwa v[234:235], v114 src0_sel:WORD_1
	v_cvt_pk_f32_fp8_e32 v[236:237], v115
	v_cvt_pk_f32_fp8_sdwa v[238:239], v115 src0_sel:WORD_1
	v_pk_fma_f32 v[48:49], v[224:225], s[24:25], v[48:49] op_sel_hi:[1,0,1]
	v_pk_fma_f32 v[50:51], v[226:227], s[24:25], v[50:51] op_sel_hi:[1,0,1]
	v_pk_fma_f32 v[52:53], v[228:229], s[24:25], v[52:53] op_sel_hi:[1,0,1]
	v_pk_fma_f32 v[54:55], v[230:231], s[24:25], v[54:55] op_sel_hi:[1,0,1]
	v_pk_fma_f32 v[56:57], v[232:233], s[24:25], v[56:57] op_sel_hi:[1,0,1]
	v_pk_fma_f32 v[58:59], v[234:235], s[24:25], v[58:59] op_sel_hi:[1,0,1]
	v_pk_fma_f32 v[60:61], v[236:237], s[24:25], v[60:61] op_sel_hi:[1,0,1]
	v_pk_fma_f32 v[62:63], v[238:239], s[24:25], v[62:63] op_sel_hi:[1,0,1]
	v_cvt_pk_f32_fp8_e32 v[224:225], v116
	v_cvt_pk_f32_fp8_sdwa v[226:227], v116 src0_sel:WORD_1
	v_cvt_pk_f32_fp8_e32 v[228:229], v117
	v_cvt_pk_f32_fp8_sdwa v[230:231], v117 src0_sel:WORD_1
	v_cvt_pk_f32_fp8_e32 v[232:233], v118
	v_cvt_pk_f32_fp8_sdwa v[234:235], v118 src0_sel:WORD_1
	v_cvt_pk_f32_fp8_e32 v[236:237], v119
	v_cvt_pk_f32_fp8_sdwa v[238:239], v119 src0_sel:WORD_1
	v_pk_fma_f32 v[48:49], v[224:225], s[26:27], v[48:49] op_sel_hi:[1,0,1]
	v_pk_fma_f32 v[50:51], v[226:227], s[26:27], v[50:51] op_sel_hi:[1,0,1]
	v_pk_fma_f32 v[52:53], v[228:229], s[26:27], v[52:53] op_sel_hi:[1,0,1]
	v_pk_fma_f32 v[54:55], v[230:231], s[26:27], v[54:55] op_sel_hi:[1,0,1]
	v_pk_fma_f32 v[56:57], v[232:233], s[26:27], v[56:57] op_sel_hi:[1,0,1]
	v_pk_fma_f32 v[58:59], v[234:235], s[26:27], v[58:59] op_sel_hi:[1,0,1]
; DI void peer_item_v(const Params& p, int item) {
;     ...
;     float* orow = p.out + tok * 1024 + lane * 4;
;     float4 y[4];
;     float ss = 0.f;
; #pragma unroll
;     for (int i = 0; i < 4; ++i) {
;       y[i] = *(const float4*)(orow + 256 * i);
;       y[i].x += out[4 * i]; y[i].y += out[4 * i + 1]; y[i].z += out[4 * i + 2]; y[i].w += out[4 * i + 3];
;       ss += y[i].x * y[i].x + y[i].y * y[i].y + y[i].z * y[i].z + y[i].w * y[i].w;
;     }
;     ss = wave_sum(ss);
;     const float r = rsqrtf(ss * (1.f / 1024.f) + 1e-6f);
; #pragma unroll
;     for (int i = 0; i < 4; ++i) {
;       float4 g = *(const float4*)(p.g_final + 256 * i + lane * 4);
;       y[i].x *= r * g.x; y[i].y *= r * g.y; y[i].z *= r * g.z; y[i].w *= r * g.w;
;       *(float4*)(orow + 256 * i) = y[i];
;     }
	v_pk_fma_f32 v[60:61], v[236:237], s[26:27], v[60:61] op_sel_hi:[1,0,1]
	v_pk_fma_f32 v[62:63], v[238:239], s[26:27], v[62:63] op_sel_hi:[1,0,1]
	v_cvt_pk_f32_fp8_e32 v[224:225], v120
	v_cvt_pk_f32_fp8_sdwa v[226:227], v120 src0_sel:WORD_1
	v_cvt_pk_f32_fp8_e32 v[228:229], v121
	v_cvt_pk_f32_fp8_sdwa v[230:231], v121 src0_sel:WORD_1
	v_cvt_pk_f32_fp8_e32 v[232:233], v122
	v_cvt_pk_f32_fp8_sdwa v[234:235], v122 src0_sel:WORD_1
	v_cvt_pk_f32_fp8_e32 v[236:237], v123
	v_cvt_pk_f32_fp8_sdwa v[238:239], v123 src0_sel:WORD_1
	v_pk_fma_f32 v[48:49], v[224:225], s[28:29], v[48:49] op_sel_hi:[1,0,1]
	v_pk_fma_f32 v[50:51], v[226:227], s[28:29], v[50:51] op_sel_hi:[1,0,1]
	v_pk_fma_f32 v[52:53], v[228:229], s[28:29], v[52:53] op_sel_hi:[1,0,1]
	v_pk_fma_f32 v[54:55], v[230:231], s[28:29], v[54:55] op_sel_hi:[1,0,1]
	v_pk_fma_f32 v[56:57], v[232:233], s[28:29], v[56:57] op_sel_hi:[1,0,1]
	v_pk_fma_f32 v[58:59], v[234:235], s[28:29], v[58:59] op_sel_hi:[1,0,1]
	v_pk_fma_f32 v[60:61], v[236:237], s[28:29], v[60:61] op_sel_hi:[1,0,1]
	v_pk_fma_f32 v[62:63], v[238:239], s[28:29], v[62:63] op_sel_hi:[1,0,1]
	v_cvt_pk_f32_fp8_e32 v[224:225], v124
	v_cvt_pk_f32_fp8_sdwa v[226:227], v124 src0_sel:WORD_1
	v_cvt_pk_f32_fp8_e32 v[228:229], v125
	v_cvt_pk_f32_fp8_sdwa v[230:231], v125 src0_sel:WORD_1
	v_cvt_pk_f32_fp8_e32 v[232:233], v126
	v_cvt_pk_f32_fp8_sdwa v[234:235], v126 src0_sel:WORD_1
	v_cvt_pk_f32_fp8_e32 v[236:237], v127
	v_cvt_pk_f32_fp8_sdwa v[238:239], v127 src0_sel:WORD_1
	v_pk_fma_f32 v[48:49], v[224:225], s[30:31], v[48:49] op_sel_hi:[1,0,1]
	v_pk_fma_f32 v[50:51], v[226:227], s[30:31], v[50:51] op_sel_hi:[1,0,1]
	v_pk_fma_f32 v[52:53], v[228:229], s[30:31], v[52:53] op_sel_hi:[1,0,1]
	v_pk_fma_f32 v[54:55], v[230:231], s[30:31], v[54:55] op_sel_hi:[1,0,1]
	v_pk_fma_f32 v[56:57], v[232:233], s[30:31], v[56:57] op_sel_hi:[1,0,1]
	v_pk_fma_f32 v[58:59], v[234:235], s[30:31], v[58:59] op_sel_hi:[1,0,1]
	v_pk_fma_f32 v[60:61], v[236:237], s[30:31], v[60:61] op_sel_hi:[1,0,1]
	v_pk_fma_f32 v[62:63], v[238:239], s[30:31], v[62:63] op_sel_hi:[1,0,1]
	s_mov_b32 s72, s80
	s_mov_b32 s73, s81
	s_mov_b32 s74, s82
	s_mov_b32 s75, s83
	s_mov_b32 s76, s84
	s_mov_b32 s77, s85
	s_mov_b32 s78, s86
	s_mov_b32 s79, s87
	s_add_u32 s80, s80, 8
	s_add_u32 s81, s81, 8
	s_add_u32 s82, s82, 8
	s_add_u32 s83, s83, 8
	s_add_u32 s84, s84, 8
	s_add_u32 s85, s85, 8
	s_add_u32 s86, s86, 8
	s_add_u32 s87, s87, 8
	s_and_b32 s80, s80, 63
	s_and_b32 s81, s81, 63
	s_and_b32 s82, s82, 63
	s_and_b32 s83, s83, 63
	s_and_b32 s84, s84, 63
	s_and_b32 s85, s85, 63
	s_and_b32 s86, s86, 63
	s_and_b32 s87, s87, 63
	s_add_u32 s12, s12, 1
	s_cmp_lt_u32 s12, 8
	s_cbranch_scc1 .Lvq_kA
	s_waitcnt vmcnt(0)
	global_load_dwordx4 v[128:131], v240, s[8:9]
	global_load_dwordx4 v[132:135], v240, s[8:9] offset:1024
	global_load_dwordx4 v[136:139], v240, s[8:9] offset:2048
	global_load_dwordx4 v[140:143], v240, s[8:9] offset:3072
	s_add_u32 s32, s62, 0
	s_addc_u32 s33, s63, 0
	s_add_u32 s34, s62, 4096
	s_addc_u32 s35, s63, 0
	s_add_u32 s36, s62, 8192
	s_addc_u32 s37, s63, 0
	s_add_u32 s38, s62, 12288
	s_addc_u32 s39, s63, 0
	s_waitcnt vmcnt(0)
	v_pk_add_f32 v[160:161], v[160:161], v[0:1]
	v_pk_add_f32 v[162:163], v[162:163], v[2:3]
	v_pk_add_f32 v[164:165], v[164:165], v[4:5]
	v_pk_add_f32 v[166:167], v[166:167], v[6:7]
	v_pk_add_f32 v[168:169], v[168:169], v[8:9]
	v_pk_add_f32 v[170:171], v[170:171], v[10:11]
	v_pk_add_f32 v[172:173], v[172:173], v[12:13]
	v_pk_add_f32 v[174:175], v[174:175], v[14:15]
	v_pk_mul_f32 v[224:225], v[160:161], v[160:161]
	v_pk_mul_f32 v[226:227], v[162:163], v[162:163]
	v_pk_fma_f32 v[224:225], v[164:165], v[164:165], v[224:225]
	v_pk_fma_f32 v[226:227], v[166:167], v[166:167], v[226:227]
	v_pk_fma_f32 v[224:225], v[168:169], v[168:169], v[224:225]
	v_pk_fma_f32 v[226:227], v[170:171], v[170:171], v[226:227]
	v_pk_fma_f32 v[224:225], v[172:173], v[172:173], v[224:225]
	v_pk_fma_f32 v[226:227], v[174:175], v[174:175], v[226:227]
	v_pk_add_f32 v[224:225], v[224:225], v[226:227]
	s_nop 0
	v_add_f32_e32 v224, v224, v225
	s_nop 1
	v_add_f32_dpp v224, v224, v224 row_ror:8 row_mask:0xf bank_mask:0xf
	s_nop 1
	v_add_f32_dpp v224, v224, v224 row_ror:4 row_mask:0xf bank_mask:0xf
	s_nop 1
	v_add_f32_dpp v224, v224, v224 row_ror:2 row_mask:0xf bank_mask:0xf
	s_nop 1
	v_add_f32_dpp v224, v224, v224 row_ror:1 row_mask:0xf bank_mask:0xf
	s_nop 1
	v_add_f32_dpp v224, v224, v224 row_bcast:15 row_mask:0xa bank_mask:0xf
	s_nop 1
	v_add_f32_dpp v224, v224, v224 row_bcast:31 row_mask:0xc bank_mask:0xf
	s_nop 1
	v_readlane_b32 s15, v224, 63
	s_nop 3
	v_mov_b32_e32 v224, s15
	v_fmamk_f32 v224, v224, 0x3a800000, v248
	v_rsq_f32_e32 v224, v224
	s_nop 1
	v_pk_mul_f32 v[226:227], v[128:129], v[224:225] op_sel_hi:[1,0]
	v_pk_mul_f32 v[160:161], v[160:161], v[226:227]
	v_pk_mul_f32 v[228:229], v[130:131], v[224:225] op_sel_hi:[1,0]
	v_pk_mul_f32 v[162:163], v[162:163], v[228:229]
	v_pk_mul_f32 v[230:231], v[132:133], v[224:225] op_sel_hi:[1,0]
	v_pk_mul_f32 v[164:165], v[164:165], v[230:231]
	v_pk_mul_f32 v[232:233], v[134:135], v[224:225] op_sel_hi:[1,0]
	v_pk_mul_f32 v[166:167], v[166:167], v[232:233]
	v_pk_mul_f32 v[226:227], v[136:137], v[224:225] op_sel_hi:[1,0]
	v_pk_mul_f32 v[168:169], v[168:169], v[226:227]
	v_pk_mul_f32 v[228:229], v[138:139], v[224:225] op_sel_hi:[1,0]
	v_pk_mul_f32 v[170:171], v[170:171], v[228:229]
	v_pk_mul_f32 v[230:231], v[140:141], v[224:225] op_sel_hi:[1,0]
	v_pk_mul_f32 v[172:173], v[172:173], v[230:231]
	v_pk_mul_f32 v[232:233], v[142:143], v[224:225] op_sel_hi:[1,0]
	v_pk_mul_f32 v[174:175], v[174:175], v[232:233]
	v_pk_add_f32 v[176:177], v[176:177], v[16:17]
; DI void peer_item_v(const Params& p, int item) {
;     ...
;     float4 y[4];
;     float ss = 0.f;
; #pragma unroll
;     for (int i = 0; i < 4; ++i) {
;       y[i] = *(const float4*)(orow + 256 * i);
;       y[i].x += out[4 * i]; y[i].y += out[4 * i + 1]; y[i].z += out[4 * i + 2]; y[i].w += out[4 * i + 3];
;       ss += y[i].x * y[i].x + y[i].y * y[i].y + y[i].z * y[i].z + y[i].w * y[i].w;
;     }
;     ss = wave_sum(ss);
;     const float r = rsqrtf(ss * (1.f / 1024.f) + 1e-6f);
; #pragma unroll
;     for (int i = 0; i < 4; ++i) {
;       float4 g = *(const float4*)(p.g_final + 256 * i + lane * 4);
;       y[i].x *= r * g.x; y[i].y *= r * g.y; y[i].z *= r * g.z; y[i].w *= r * g.w;
;       *(float4*)(orow + 256 * i) = y[i];
;     }
	v_pk_add_f32 v[178:179], v[178:179], v[18:19]
	v_pk_add_f32 v[180:181], v[180:181], v[20:21]
	v_pk_add_f32 v[182:183], v[182:183], v[22:23]
	v_pk_add_f32 v[184:185], v[184:185], v[24:25]
	v_pk_add_f32 v[186:187], v[186:187], v[26:27]
	v_pk_add_f32 v[188:189], v[188:189], v[28:29]
	v_pk_add_f32 v[190:191], v[190:191], v[30:31]
	v_pk_mul_f32 v[224:225], v[176:177], v[176:177]
	v_pk_mul_f32 v[226:227], v[178:179], v[178:179]
	v_pk_fma_f32 v[224:225], v[180:181], v[180:181], v[224:225]
	v_pk_fma_f32 v[226:227], v[182:183], v[182:183], v[226:227]
	v_pk_fma_f32 v[224:225], v[184:185], v[184:185], v[224:225]
	v_pk_fma_f32 v[226:227], v[186:187], v[186:187], v[226:227]
	v_pk_fma_f32 v[224:225], v[188:189], v[188:189], v[224:225]
	v_pk_fma_f32 v[226:227], v[190:191], v[190:191], v[226:227]
	v_pk_add_f32 v[224:225], v[224:225], v[226:227]
	s_nop 0
	v_add_f32_e32 v224, v224, v225
	s_nop 1
	v_add_f32_dpp v224, v224, v224 row_ror:8 row_mask:0xf bank_mask:0xf
	s_nop 1
	v_add_f32_dpp v224, v224, v224 row_ror:4 row_mask:0xf bank_mask:0xf
	s_nop 1
	v_add_f32_dpp v224, v224, v224 row_ror:2 row_mask:0xf bank_mask:0xf
	s_nop 1
	v_add_f32_dpp v224, v224, v224 row_ror:1 row_mask:0xf bank_mask:0xf
	s_nop 1
	v_add_f32_dpp v224, v224, v224 row_bcast:15 row_mask:0xa bank_mask:0xf
	s_nop 1
	v_add_f32_dpp v224, v224, v224 row_bcast:31 row_mask:0xc bank_mask:0xf
	s_nop 1
	v_readlane_b32 s15, v224, 63
	s_nop 3
	v_mov_b32_e32 v224, s15
	v_fmamk_f32 v224, v224, 0x3a800000, v248
	v_rsq_f32_e32 v224, v224
	s_nop 1
	v_pk_mul_f32 v[226:227], v[128:129], v[224:225] op_sel_hi:[1,0]
	v_pk_mul_f32 v[176:177], v[176:177], v[226:227]
	v_pk_mul_f32 v[228:229], v[130:131], v[224:225] op_sel_hi:[1,0]
	v_pk_mul_f32 v[178:179], v[178:179], v[228:229]
	v_pk_mul_f32 v[230:231], v[132:133], v[224:225] op_sel_hi:[1,0]
	v_pk_mul_f32 v[180:181], v[180:181], v[230:231]
	v_pk_mul_f32 v[232:233], v[134:135], v[224:225] op_sel_hi:[1,0]
	v_pk_mul_f32 v[182:183], v[182:183], v[232:233]
	v_pk_mul_f32 v[226:227], v[136:137], v[224:225] op_sel_hi:[1,0]
	v_pk_mul_f32 v[184:185], v[184:185], v[226:227]
	v_pk_mul_f32 v[228:229], v[138:139], v[224:225] op_sel_hi:[1,0]
	v_pk_mul_f32 v[186:187], v[186:187], v[228:229]
	v_pk_mul_f32 v[230:231], v[140:141], v[224:225] op_sel_hi:[1,0]
	v_pk_mul_f32 v[188:189], v[188:189], v[230:231]
	v_pk_mul_f32 v[232:233], v[142:143], v[224:225] op_sel_hi:[1,0]
	v_pk_mul_f32 v[190:191], v[190:191], v[232:233]
	v_pk_add_f32 v[192:193], v[192:193], v[32:33]
	v_pk_add_f32 v[194:195], v[194:195], v[34:35]
	v_pk_add_f32 v[196:197], v[196:197], v[36:37]
	v_pk_add_f32 v[198:199], v[198:199], v[38:39]
	v_pk_add_f32 v[200:201], v[200:201], v[40:41]
	v_pk_add_f32 v[202:203], v[202:203], v[42:43]
	v_pk_add_f32 v[204:205], v[204:205], v[44:45]
	v_pk_add_f32 v[206:207], v[206:207], v[46:47]
	v_pk_mul_f32 v[224:225], v[192:193], v[192:193]
	v_pk_mul_f32 v[226:227], v[194:195], v[194:195]
	v_pk_fma_f32 v[224:225], v[196:197], v[196:197], v[224:225]
	v_pk_fma_f32 v[226:227], v[198:199], v[198:199], v[226:227]
	v_pk_fma_f32 v[224:225], v[200:201], v[200:201], v[224:225]
	v_pk_fma_f32 v[226:227], v[202:203], v[202:203], v[226:227]
	v_pk_fma_f32 v[224:225], v[204:205], v[204:205], v[224:225]
	v_pk_fma_f32 v[226:227], v[206:207], v[206:207], v[226:227]
	v_pk_add_f32 v[224:225], v[224:225], v[226:227]
	s_nop 0
	v_add_f32_e32 v224, v224, v225
	s_nop 1
	v_add_f32_dpp v224, v224, v224 row_ror:8 row_mask:0xf bank_mask:0xf
	s_nop 1
	v_add_f32_dpp v224, v224, v224 row_ror:4 row_mask:0xf bank_mask:0xf
	s_nop 1
	v_add_f32_dpp v224, v224, v224 row_ror:2 row_mask:0xf bank_mask:0xf
	s_nop 1
	v_add_f32_dpp v224, v224, v224 row_ror:1 row_mask:0xf bank_mask:0xf
	s_nop 1
	v_add_f32_dpp v224, v224, v224 row_bcast:15 row_mask:0xa bank_mask:0xf
	s_nop 1
	v_add_f32_dpp v224, v224, v224 row_bcast:31 row_mask:0xc bank_mask:0xf
	s_nop 1
	v_readlane_b32 s15, v224, 63
	s_nop 3
	v_mov_b32_e32 v224, s15
	v_fmamk_f32 v224, v224, 0x3a800000, v248
	v_rsq_f32_e32 v224, v224
	s_nop 1
	v_pk_mul_f32 v[226:227], v[128:129], v[224:225] op_sel_hi:[1,0]
	v_pk_mul_f32 v[192:193], v[192:193], v[226:227]
	v_pk_mul_f32 v[228:229], v[130:131], v[224:225] op_sel_hi:[1,0]
	v_pk_mul_f32 v[194:195], v[194:195], v[228:229]
	v_pk_mul_f32 v[230:231], v[132:133], v[224:225] op_sel_hi:[1,0]
	v_pk_mul_f32 v[196:197], v[196:197], v[230:231]
	v_pk_mul_f32 v[232:233], v[134:135], v[224:225] op_sel_hi:[1,0]
	v_pk_mul_f32 v[198:199], v[198:199], v[232:233]
	v_pk_mul_f32 v[226:227], v[136:137], v[224:225] op_sel_hi:[1,0]
	v_pk_mul_f32 v[200:201], v[200:201], v[226:227]
	v_pk_mul_f32 v[228:229], v[138:139], v[224:225] op_sel_hi:[1,0]
	v_pk_mul_f32 v[202:203], v[202:203], v[228:229]
	v_pk_mul_f32 v[230:231], v[140:141], v[224:225] op_sel_hi:[1,0]
	v_pk_mul_f32 v[204:205], v[204:205], v[230:231]
	v_pk_mul_f32 v[232:233], v[142:143], v[224:225] op_sel_hi:[1,0]
	v_pk_mul_f32 v[206:207], v[206:207], v[232:233]
	v_pk_add_f32 v[208:209], v[208:209], v[48:49]
	v_pk_add_f32 v[210:211], v[210:211], v[50:51]
	v_pk_add_f32 v[212:213], v[212:213], v[52:53]
	v_pk_add_f32 v[214:215], v[214:215], v[54:55]
	v_pk_add_f32 v[216:217], v[216:217], v[56:57]
	v_pk_add_f32 v[218:219], v[218:219], v[58:59]
	v_pk_add_f32 v[220:221], v[220:221], v[60:61]
	v_pk_add_f32 v[222:223], v[222:223], v[62:63]
	v_pk_mul_f32 v[224:225], v[208:209], v[208:209]
	v_pk_mul_f32 v[226:227], v[210:211], v[210:211]
	v_pk_fma_f32 v[224:225], v[212:213], v[212:213], v[224:225]
	v_pk_fma_f32 v[226:227], v[214:215], v[214:215], v[226:227]
	v_pk_fma_f32 v[224:225], v[216:217], v[216:217], v[224:225]
	v_pk_fma_f32 v[226:227], v[218:219], v[218:219], v[226:227]
	v_pk_fma_f32 v[224:225], v[220:221], v[220:221], v[224:225]
; DI void peer_item_v(const Params& p, int item) {
;     ...
;     float out[16];
; #pragma unroll
;     for (int i = 0; i < 16; ++i) out[i] = 0.f;
;     ...
;     for (int i = 0; i < 4; ++i) {
;       y[i] = *(const float4*)(orow + 256 * i);
;       y[i].x += out[4 * i]; y[i].y += out[4 * i + 1]; y[i].z += out[4 * i + 2]; y[i].w += out[4 * i + 3];
;       ss += y[i].x * y[i].x + y[i].y * y[i].y + y[i].z * y[i].z + y[i].w * y[i].w;
;     }
;     ss = wave_sum(ss);
;     const float r = rsqrtf(ss * (1.f / 1024.f) + 1e-6f);
; #pragma unroll
;     for (int i = 0; i < 4; ++i) {
;       float4 g = *(const float4*)(p.g_final + 256 * i + lane * 4);
;       y[i].x *= r * g.x; y[i].y *= r * g.y; y[i].z *= r * g.z; y[i].w *= r * g.w;
;       *(float4*)(orow + 256 * i) = y[i];
;     }
	v_pk_fma_f32 v[226:227], v[222:223], v[222:223], v[226:227]
	v_pk_add_f32 v[224:225], v[224:225], v[226:227]
	s_nop 0
	v_add_f32_e32 v224, v224, v225
	s_nop 1
	v_add_f32_dpp v224, v224, v224 row_ror:8 row_mask:0xf bank_mask:0xf
	s_nop 1
	v_add_f32_dpp v224, v224, v224 row_ror:4 row_mask:0xf bank_mask:0xf
	s_nop 1
	v_add_f32_dpp v224, v224, v224 row_ror:2 row_mask:0xf bank_mask:0xf
	s_nop 1
	v_add_f32_dpp v224, v224, v224 row_ror:1 row_mask:0xf bank_mask:0xf
	s_nop 1
	v_add_f32_dpp v224, v224, v224 row_bcast:15 row_mask:0xa bank_mask:0xf
	s_nop 1
	v_add_f32_dpp v224, v224, v224 row_bcast:31 row_mask:0xc bank_mask:0xf
	s_nop 1
	v_readlane_b32 s15, v224, 63
	s_nop 3
	v_mov_b32_e32 v224, s15
	v_fmamk_f32 v224, v224, 0x3a800000, v248
	v_rsq_f32_e32 v224, v224
	s_nop 1
	v_pk_mul_f32 v[226:227], v[128:129], v[224:225] op_sel_hi:[1,0]
	v_pk_mul_f32 v[208:209], v[208:209], v[226:227]
	v_pk_mul_f32 v[228:229], v[130:131], v[224:225] op_sel_hi:[1,0]
	v_pk_mul_f32 v[210:211], v[210:211], v[228:229]
	v_pk_mul_f32 v[230:231], v[132:133], v[224:225] op_sel_hi:[1,0]
	v_pk_mul_f32 v[212:213], v[212:213], v[230:231]
	v_pk_mul_f32 v[232:233], v[134:135], v[224:225] op_sel_hi:[1,0]
	v_pk_mul_f32 v[214:215], v[214:215], v[232:233]
	v_pk_mul_f32 v[226:227], v[136:137], v[224:225] op_sel_hi:[1,0]
	v_pk_mul_f32 v[216:217], v[216:217], v[226:227]
	v_pk_mul_f32 v[228:229], v[138:139], v[224:225] op_sel_hi:[1,0]
	v_pk_mul_f32 v[218:219], v[218:219], v[228:229]
	v_pk_mul_f32 v[230:231], v[140:141], v[224:225] op_sel_hi:[1,0]
	v_pk_mul_f32 v[220:221], v[220:221], v[230:231]
	v_pk_mul_f32 v[232:233], v[142:143], v[224:225] op_sel_hi:[1,0]
	v_pk_mul_f32 v[222:223], v[222:223], v[232:233]
	global_store_dwordx4 v240, v[160:163], s[32:33]
	global_store_dwordx4 v240, v[164:167], s[32:33] offset:1024
	global_store_dwordx4 v240, v[168:171], s[32:33] offset:2048
	global_store_dwordx4 v240, v[172:175], s[32:33] offset:3072
	global_store_dwordx4 v240, v[176:179], s[34:35]
	global_store_dwordx4 v240, v[180:183], s[34:35] offset:1024
	global_store_dwordx4 v240, v[184:187], s[34:35] offset:2048
	global_store_dwordx4 v240, v[188:191], s[34:35] offset:3072
	global_store_dwordx4 v240, v[192:195], s[36:37]
	global_store_dwordx4 v240, v[196:199], s[36:37] offset:1024
	global_store_dwordx4 v240, v[200:203], s[36:37] offset:2048
	global_store_dwordx4 v240, v[204:207], s[36:37] offset:3072
	global_store_dwordx4 v240, v[208:211], s[38:39]
	global_store_dwordx4 v240, v[212:215], s[38:39] offset:1024
	global_store_dwordx4 v240, v[216:219], s[38:39] offset:2048
	global_store_dwordx4 v240, v[220:223], s[38:39] offset:3072
	s_nop 1
	v_mov_b32_e32 v64, 0
	v_mov_b32_e32 v65, 0
	v_mov_b32_e32 v66, 0
	v_mov_b32_e32 v67, 0
	v_mov_b32_e32 v68, 0
	v_mov_b32_e32 v69, 0
	v_mov_b32_e32 v70, 0
	v_mov_b32_e32 v71, 0
	v_mov_b32_e32 v72, 0
	v_mov_b32_e32 v73, 0
	v_mov_b32_e32 v74, 0
	v_mov_b32_e32 v75, 0
	v_mov_b32_e32 v76, 0
	v_mov_b32_e32 v77, 0
	v_mov_b32_e32 v78, 0
	v_mov_b32_e32 v79, 0
	v_mov_b32_e32 v80, 0
	v_mov_b32_e32 v81, 0
	v_mov_b32_e32 v82, 0
	v_mov_b32_e32 v83, 0
	v_mov_b32_e32 v84, 0
	v_mov_b32_e32 v85, 0
	v_mov_b32_e32 v86, 0
	v_mov_b32_e32 v87, 0
	v_mov_b32_e32 v88, 0
	v_mov_b32_e32 v89, 0
	v_mov_b32_e32 v90, 0
	v_mov_b32_e32 v91, 0
	v_mov_b32_e32 v92, 0
	v_mov_b32_e32 v93, 0
	v_mov_b32_e32 v94, 0
	v_mov_b32_e32 v95, 0
	v_mov_b32_e32 v96, 0
	v_mov_b32_e32 v97, 0
	v_mov_b32_e32 v98, 0
	v_mov_b32_e32 v99, 0
	v_mov_b32_e32 v100, 0
	v_mov_b32_e32 v101, 0
	v_mov_b32_e32 v102, 0
	v_mov_b32_e32 v103, 0
	v_mov_b32_e32 v104, 0
	v_mov_b32_e32 v105, 0
	v_mov_b32_e32 v106, 0
	v_mov_b32_e32 v107, 0
	v_mov_b32_e32 v108, 0
	v_mov_b32_e32 v109, 0
	v_mov_b32_e32 v110, 0
	v_mov_b32_e32 v111, 0
	v_mov_b32_e32 v112, 0
	v_mov_b32_e32 v113, 0
	v_mov_b32_e32 v114, 0
	v_mov_b32_e32 v115, 0
; DI void peer_item_v(const Params& p, int item) {
;     ...
;     float out[16];
; #pragma unroll
;     for (int i = 0; i < 16; ++i) out[i] = 0.f;
;     u32x4 vqa[8], vqb[8];
	v_mov_b32_e32 v116, 0
	v_mov_b32_e32 v117, 0
	v_mov_b32_e32 v118, 0
	v_mov_b32_e32 v119, 0
	v_mov_b32_e32 v120, 0
	v_mov_b32_e32 v121, 0
	v_mov_b32_e32 v122, 0
	v_mov_b32_e32 v123, 0
	v_mov_b32_e32 v124, 0
	v_mov_b32_e32 v125, 0
	v_mov_b32_e32 v126, 0
	v_mov_b32_e32 v127, 0
	s_add_u32 s88, s62, 16384
	s_addc_u32 s89, s63, 0
	s_add_u32 s90, s62, 20480
	s_addc_u32 s91, s63, 0
	s_add_u32 s92, s62, 24576
	s_addc_u32 s93, s63, 0
	s_add_u32 s94, s62, 28672
	s_addc_u32 s95, s63, 0
	s_mov_b32 s72, 0
	s_mov_b32 s73, 1
	s_mov_b32 s74, 2
	s_mov_b32 s75, 3
	s_mov_b32 s76, 4
	s_mov_b32 s77, 5
	s_mov_b32 s78, 6
	s_mov_b32 s79, 7
	s_mov_b32 s80, 8
	s_mov_b32 s81, 9
	s_mov_b32 s82, 10
	s_mov_b32 s83, 11
	s_mov_b32 s84, 12
	s_mov_b32 s85, 13
	s_mov_b32 s86, 14
	s_mov_b32 s87, 15
	s_nop 0
	v_readlane_b32 s48, v144, s72
	v_readlane_b32 s49, v144, s73
	v_readlane_b32 s50, v144, s74
	v_readlane_b32 s51, v144, s75
	v_readlane_b32 s52, v144, s76
	v_readlane_b32 s53, v144, s77
	v_readlane_b32 s54, v144, s78
	v_readlane_b32 s55, v144, s79
	s_add_u32 s32, s0, s48
	s_addc_u32 s33, s1, 0
	s_add_u32 s34, s0, s49
	s_addc_u32 s35, s1, 0
	s_add_u32 s36, s0, s50
	s_addc_u32 s37, s1, 0
	s_add_u32 s38, s0, s51
	s_addc_u32 s39, s1, 0
	s_add_u32 s40, s0, s52
	s_addc_u32 s41, s1, 0
	s_add_u32 s42, s0, s53
	s_addc_u32 s43, s1, 0
	s_add_u32 s44, s0, s54
	s_addc_u32 s45, s1, 0
	s_add_u32 s46, s0, s55
	s_addc_u32 s47, s1, 0
	global_load_dwordx4 v[160:163], v240, s[32:33]
	global_load_dwordx4 v[164:167], v240, s[34:35]
	global_load_dwordx4 v[168:171], v240, s[36:37]
	global_load_dwordx4 v[172:175], v240, s[38:39]
	global_load_dwordx4 v[176:179], v240, s[40:41]
	global_load_dwordx4 v[180:183], v240, s[42:43]
	global_load_dwordx4 v[184:187], v240, s[44:45]
	global_load_dwordx4 v[188:191], v240, s[46:47]
	v_readlane_b32 s48, v148, s72
	v_readlane_b32 s49, v148, s73
	v_readlane_b32 s50, v148, s74
	v_readlane_b32 s51, v148, s75
	v_readlane_b32 s52, v148, s76
	v_readlane_b32 s53, v148, s77
	v_readlane_b32 s54, v148, s78
	v_readlane_b32 s55, v148, s79
	s_add_u32 s32, s0, s48
	s_addc_u32 s33, s1, 0
	s_add_u32 s34, s0, s49
	s_addc_u32 s35, s1, 0
	s_add_u32 s36, s0, s50
	s_addc_u32 s37, s1, 0
	s_add_u32 s38, s0, s51
	s_addc_u32 s39, s1, 0
	s_add_u32 s40, s0, s52
	s_addc_u32 s41, s1, 0
	s_add_u32 s42, s0, s53
	s_addc_u32 s43, s1, 0
	s_add_u32 s44, s0, s54
	s_addc_u32 s45, s1, 0
	s_add_u32 s46, s0, s55
	s_addc_u32 s47, s1, 0
	global_load_dwordx4 v[192:195], v240, s[32:33]
	global_load_dwordx4 v[196:199], v240, s[34:35]
	global_load_dwordx4 v[200:203], v240, s[36:37]
	global_load_dwordx4 v[204:207], v240, s[38:39]
	global_load_dwordx4 v[208:211], v240, s[40:41]
	global_load_dwordx4 v[212:215], v240, s[42:43]
	global_load_dwordx4 v[216:219], v240, s[44:45]
	global_load_dwordx4 v[220:223], v240, s[46:47]
	v_readlane_b32 s48, v152, s72
	v_readlane_b32 s49, v152, s73
	v_readlane_b32 s50, v152, s74
	v_readlane_b32 s51, v152, s75
	v_readlane_b32 s52, v152, s76
	v_readlane_b32 s53, v152, s77
	v_readlane_b32 s54, v152, s78
	v_readlane_b32 s55, v152, s79
	s_add_u32 s32, s0, s48
	s_addc_u32 s33, s1, 0
	s_add_u32 s34, s0, s49
	s_addc_u32 s35, s1, 0
	s_add_u32 s36, s0, s50
	s_addc_u32 s37, s1, 0
	s_add_u32 s38, s0, s51
	s_addc_u32 s39, s1, 0
	s_add_u32 s40, s0, s52
	s_addc_u32 s41, s1, 0
	s_add_u32 s42, s0, s53
	s_addc_u32 s43, s1, 0
	s_add_u32 s44, s0, s54
	s_addc_u32 s45, s1, 0
	s_add_u32 s46, s0, s55
	s_addc_u32 s47, s1, 0
	global_load_dwordx4 v[0:3], v240, s[32:33]
	global_load_dwordx4 v[4:7], v240, s[34:35]
	global_load_dwordx4 v[8:11], v240, s[36:37]
	global_load_dwordx4 v[12:15], v240, s[38:39]
	global_load_dwordx4 v[16:19], v240, s[40:41]
	global_load_dwordx4 v[20:23], v240, s[42:43]
	global_load_dwordx4 v[24:27], v240, s[44:45]
	global_load_dwordx4 v[28:31], v240, s[46:47]
	s_mov_b32 s12, 0

.Lvd_cons7_Lvq_kB:
	v_cvt_pk_f32_fp8_e32 v[224:225], v32
	v_cvt_pk_f32_fp8_sdwa v[226:227], v32 src0_sel:WORD_1
	v_cvt_pk_f32_fp8_e32 v[228:229], v33
	v_cvt_pk_f32_fp8_sdwa v[230:231], v33 src0_sel:WORD_1
	v_cvt_pk_f32_fp8_e32 v[232:233], v34
	v_cvt_pk_f32_fp8_sdwa v[234:235], v34 src0_sel:WORD_1
	v_cvt_pk_f32_fp8_e32 v[236:237], v35
	v_cvt_pk_f32_fp8_sdwa v[238:239], v35 src0_sel:WORD_1
	v_pk_fma_f32 v[112:113], v[224:225], s[16:17], v[112:113] op_sel_hi:[1,0,1]
	v_pk_fma_f32 v[114:115], v[226:227], s[16:17], v[114:115] op_sel_hi:[1,0,1]
	v_pk_fma_f32 v[116:117], v[228:229], s[16:17], v[116:117] op_sel_hi:[1,0,1]
	v_pk_fma_f32 v[118:119], v[230:231], s[16:17], v[118:119] op_sel_hi:[1,0,1]
	v_pk_fma_f32 v[120:121], v[232:233], s[16:17], v[120:121] op_sel_hi:[1,0,1]
	v_pk_fma_f32 v[122:123], v[234:235], s[16:17], v[122:123] op_sel_hi:[1,0,1]
	v_pk_fma_f32 v[124:125], v[236:237], s[16:17], v[124:125] op_sel_hi:[1,0,1]
	v_pk_fma_f32 v[126:127], v[238:239], s[16:17], v[126:127] op_sel_hi:[1,0,1]
	v_cvt_pk_f32_fp8_e32 v[224:225], v36
	v_cvt_pk_f32_fp8_sdwa v[226:227], v36 src0_sel:WORD_1
	v_cvt_pk_f32_fp8_e32 v[228:229], v37
	v_cvt_pk_f32_fp8_sdwa v[230:231], v37 src0_sel:WORD_1
	v_cvt_pk_f32_fp8_e32 v[232:233], v38
	v_cvt_pk_f32_fp8_sdwa v[234:235], v38 src0_sel:WORD_1
	v_cvt_pk_f32_fp8_e32 v[236:237], v39
	v_cvt_pk_f32_fp8_sdwa v[238:239], v39 src0_sel:WORD_1
	v_pk_fma_f32 v[112:113], v[224:225], s[18:19], v[112:113] op_sel_hi:[1,0,1]
	v_pk_fma_f32 v[114:115], v[226:227], s[18:19], v[114:115] op_sel_hi:[1,0,1]
	v_pk_fma_f32 v[116:117], v[228:229], s[18:19], v[116:117] op_sel_hi:[1,0,1]
	v_pk_fma_f32 v[118:119], v[230:231], s[18:19], v[118:119] op_sel_hi:[1,0,1]
	v_pk_fma_f32 v[120:121], v[232:233], s[18:19], v[120:121] op_sel_hi:[1,0,1]
	v_pk_fma_f32 v[122:123], v[234:235], s[18:19], v[122:123] op_sel_hi:[1,0,1]
	v_pk_fma_f32 v[124:125], v[236:237], s[18:19], v[124:125] op_sel_hi:[1,0,1]
	v_pk_fma_f32 v[126:127], v[238:239], s[18:19], v[126:127] op_sel_hi:[1,0,1]
	v_cvt_pk_f32_fp8_e32 v[224:225], v40
	v_cvt_pk_f32_fp8_sdwa v[226:227], v40 src0_sel:WORD_1
	v_cvt_pk_f32_fp8_e32 v[228:229], v41
	v_cvt_pk_f32_fp8_sdwa v[230:231], v41 src0_sel:WORD_1
	v_cvt_pk_f32_fp8_e32 v[232:233], v42
	v_cvt_pk_f32_fp8_sdwa v[234:235], v42 src0_sel:WORD_1
	v_cvt_pk_f32_fp8_e32 v[236:237], v43
	v_cvt_pk_f32_fp8_sdwa v[238:239], v43 src0_sel:WORD_1
	v_pk_fma_f32 v[112:113], v[224:225], s[20:21], v[112:113] op_sel_hi:[1,0,1]
	v_pk_fma_f32 v[114:115], v[226:227], s[20:21], v[114:115] op_sel_hi:[1,0,1]
	v_pk_fma_f32 v[116:117], v[228:229], s[20:21], v[116:117] op_sel_hi:[1,0,1]
	v_pk_fma_f32 v[118:119], v[230:231], s[20:21], v[118:119] op_sel_hi:[1,0,1]
	v_pk_fma_f32 v[120:121], v[232:233], s[20:21], v[120:121] op_sel_hi:[1,0,1]
	v_pk_fma_f32 v[122:123], v[234:235], s[20:21], v[122:123] op_sel_hi:[1,0,1]
	v_pk_fma_f32 v[124:125], v[236:237], s[20:21], v[124:125] op_sel_hi:[1,0,1]
	v_pk_fma_f32 v[126:127], v[238:239], s[20:21], v[126:127] op_sel_hi:[1,0,1]
	v_cvt_pk_f32_fp8_e32 v[224:225], v44
	v_cvt_pk_f32_fp8_sdwa v[226:227], v44 src0_sel:WORD_1
	v_cvt_pk_f32_fp8_e32 v[228:229], v45
	v_cvt_pk_f32_fp8_sdwa v[230:231], v45 src0_sel:WORD_1
	v_cvt_pk_f32_fp8_e32 v[232:233], v46
	v_cvt_pk_f32_fp8_sdwa v[234:235], v46 src0_sel:WORD_1
	v_cvt_pk_f32_fp8_e32 v[236:237], v47
	v_cvt_pk_f32_fp8_sdwa v[238:239], v47 src0_sel:WORD_1
	v_pk_fma_f32 v[112:113], v[224:225], s[22:23], v[112:113] op_sel_hi:[1,0,1]
	v_pk_fma_f32 v[114:115], v[226:227], s[22:23], v[114:115] op_sel_hi:[1,0,1]
	v_pk_fma_f32 v[116:117], v[228:229], s[22:23], v[116:117] op_sel_hi:[1,0,1]
	v_pk_fma_f32 v[118:119], v[230:231], s[22:23], v[118:119] op_sel_hi:[1,0,1]
	v_pk_fma_f32 v[120:121], v[232:233], s[22:23], v[120:121] op_sel_hi:[1,0,1]
	v_pk_fma_f32 v[122:123], v[234:235], s[22:23], v[122:123] op_sel_hi:[1,0,1]
	v_pk_fma_f32 v[124:125], v[236:237], s[22:23], v[124:125] op_sel_hi:[1,0,1]
	v_pk_fma_f32 v[126:127], v[238:239], s[22:23], v[126:127] op_sel_hi:[1,0,1]
	v_cvt_pk_f32_fp8_e32 v[224:225], v48
	v_cvt_pk_f32_fp8_sdwa v[226:227], v48 src0_sel:WORD_1
	v_cvt_pk_f32_fp8_e32 v[228:229], v49
	v_cvt_pk_f32_fp8_sdwa v[230:231], v49 src0_sel:WORD_1
	v_cvt_pk_f32_fp8_e32 v[232:233], v50
	v_cvt_pk_f32_fp8_sdwa v[234:235], v50 src0_sel:WORD_1
	v_cvt_pk_f32_fp8_e32 v[236:237], v51
	v_cvt_pk_f32_fp8_sdwa v[238:239], v51 src0_sel:WORD_1
	v_pk_fma_f32 v[112:113], v[224:225], s[24:25], v[112:113] op_sel_hi:[1,0,1]
	v_pk_fma_f32 v[114:115], v[226:227], s[24:25], v[114:115] op_sel_hi:[1,0,1]
	v_pk_fma_f32 v[116:117], v[228:229], s[24:25], v[116:117] op_sel_hi:[1,0,1]
	v_pk_fma_f32 v[118:119], v[230:231], s[24:25], v[118:119] op_sel_hi:[1,0,1]
	v_pk_fma_f32 v[120:121], v[232:233], s[24:25], v[120:121] op_sel_hi:[1,0,1]
	v_pk_fma_f32 v[122:123], v[234:235], s[24:25], v[122:123] op_sel_hi:[1,0,1]
	v_pk_fma_f32 v[124:125], v[236:237], s[24:25], v[124:125] op_sel_hi:[1,0,1]
	v_pk_fma_f32 v[126:127], v[238:239], s[24:25], v[126:127] op_sel_hi:[1,0,1]
	v_cvt_pk_f32_fp8_e32 v[224:225], v52
	v_cvt_pk_f32_fp8_sdwa v[226:227], v52 src0_sel:WORD_1
	v_cvt_pk_f32_fp8_e32 v[228:229], v53
	v_cvt_pk_f32_fp8_sdwa v[230:231], v53 src0_sel:WORD_1
	v_cvt_pk_f32_fp8_e32 v[232:233], v54
	v_cvt_pk_f32_fp8_sdwa v[234:235], v54 src0_sel:WORD_1
	v_cvt_pk_f32_fp8_e32 v[236:237], v55
	v_cvt_pk_f32_fp8_sdwa v[238:239], v55 src0_sel:WORD_1
	v_pk_fma_f32 v[112:113], v[224:225], s[26:27], v[112:113] op_sel_hi:[1,0,1]
	v_pk_fma_f32 v[114:115], v[226:227], s[26:27], v[114:115] op_sel_hi:[1,0,1]
	v_pk_fma_f32 v[116:117], v[228:229], s[26:27], v[116:117] op_sel_hi:[1,0,1]
	v_pk_fma_f32 v[118:119], v[230:231], s[26:27], v[118:119] op_sel_hi:[1,0,1]
; DI void peer_item_v(const Params& p, int item) {
;     ...
;     float4 y[4];
;     float ss = 0.f;
; #pragma unroll
;     for (int i = 0; i < 4; ++i) {
;       y[i] = *(const float4*)(orow + 256 * i);
;       y[i].x += out[4 * i]; y[i].y += out[4 * i + 1]; y[i].z += out[4 * i + 2]; y[i].w += out[4 * i + 3];
;       ss += y[i].x * y[i].x + y[i].y * y[i].y + y[i].z * y[i].z + y[i].w * y[i].w;
;     }
;     ss = wave_sum(ss);
;     const float r = rsqrtf(ss * (1.f / 1024.f) + 1e-6f);
	v_pk_fma_f32 v[120:121], v[232:233], s[26:27], v[120:121] op_sel_hi:[1,0,1]
	v_pk_fma_f32 v[122:123], v[234:235], s[26:27], v[122:123] op_sel_hi:[1,0,1]
	v_pk_fma_f32 v[124:125], v[236:237], s[26:27], v[124:125] op_sel_hi:[1,0,1]
	v_pk_fma_f32 v[126:127], v[238:239], s[26:27], v[126:127] op_sel_hi:[1,0,1]
	v_cvt_pk_f32_fp8_e32 v[224:225], v56
	v_cvt_pk_f32_fp8_sdwa v[226:227], v56 src0_sel:WORD_1
	v_cvt_pk_f32_fp8_e32 v[228:229], v57
	v_cvt_pk_f32_fp8_sdwa v[230:231], v57 src0_sel:WORD_1
	v_cvt_pk_f32_fp8_e32 v[232:233], v58
	v_cvt_pk_f32_fp8_sdwa v[234:235], v58 src0_sel:WORD_1
	v_cvt_pk_f32_fp8_e32 v[236:237], v59
	v_cvt_pk_f32_fp8_sdwa v[238:239], v59 src0_sel:WORD_1
	v_pk_fma_f32 v[112:113], v[224:225], s[28:29], v[112:113] op_sel_hi:[1,0,1]
	v_pk_fma_f32 v[114:115], v[226:227], s[28:29], v[114:115] op_sel_hi:[1,0,1]
	v_pk_fma_f32 v[116:117], v[228:229], s[28:29], v[116:117] op_sel_hi:[1,0,1]
	v_pk_fma_f32 v[118:119], v[230:231], s[28:29], v[118:119] op_sel_hi:[1,0,1]
	v_pk_fma_f32 v[120:121], v[232:233], s[28:29], v[120:121] op_sel_hi:[1,0,1]
	v_pk_fma_f32 v[122:123], v[234:235], s[28:29], v[122:123] op_sel_hi:[1,0,1]
	v_pk_fma_f32 v[124:125], v[236:237], s[28:29], v[124:125] op_sel_hi:[1,0,1]
	v_pk_fma_f32 v[126:127], v[238:239], s[28:29], v[126:127] op_sel_hi:[1,0,1]
	v_cvt_pk_f32_fp8_e32 v[224:225], v60
	v_cvt_pk_f32_fp8_sdwa v[226:227], v60 src0_sel:WORD_1
	v_cvt_pk_f32_fp8_e32 v[228:229], v61
	v_cvt_pk_f32_fp8_sdwa v[230:231], v61 src0_sel:WORD_1
	v_cvt_pk_f32_fp8_e32 v[232:233], v62
	v_cvt_pk_f32_fp8_sdwa v[234:235], v62 src0_sel:WORD_1
	v_cvt_pk_f32_fp8_e32 v[236:237], v63
	v_cvt_pk_f32_fp8_sdwa v[238:239], v63 src0_sel:WORD_1
	v_pk_fma_f32 v[112:113], v[224:225], s[30:31], v[112:113] op_sel_hi:[1,0,1]
	v_pk_fma_f32 v[114:115], v[226:227], s[30:31], v[114:115] op_sel_hi:[1,0,1]
	v_pk_fma_f32 v[116:117], v[228:229], s[30:31], v[116:117] op_sel_hi:[1,0,1]
	v_pk_fma_f32 v[118:119], v[230:231], s[30:31], v[118:119] op_sel_hi:[1,0,1]
	v_pk_fma_f32 v[120:121], v[232:233], s[30:31], v[120:121] op_sel_hi:[1,0,1]
	v_pk_fma_f32 v[122:123], v[234:235], s[30:31], v[122:123] op_sel_hi:[1,0,1]
	v_pk_fma_f32 v[124:125], v[236:237], s[30:31], v[124:125] op_sel_hi:[1,0,1]
	v_pk_fma_f32 v[126:127], v[238:239], s[30:31], v[126:127] op_sel_hi:[1,0,1]
	s_mov_b32 s72, s80
	s_mov_b32 s73, s81
	s_mov_b32 s74, s82
	s_mov_b32 s75, s83
	s_mov_b32 s76, s84
	s_mov_b32 s77, s85
	s_mov_b32 s78, s86
	s_mov_b32 s79, s87
	s_add_u32 s80, s80, 8
	s_add_u32 s81, s81, 8
	s_add_u32 s82, s82, 8
	s_add_u32 s83, s83, 8
	s_add_u32 s84, s84, 8
	s_add_u32 s85, s85, 8
	s_add_u32 s86, s86, 8
	s_add_u32 s87, s87, 8
	s_and_b32 s80, s80, 63
	s_and_b32 s81, s81, 63
	s_and_b32 s82, s82, 63
	s_and_b32 s83, s83, 63
	s_and_b32 s84, s84, 63
	s_and_b32 s85, s85, 63
	s_and_b32 s86, s86, 63
	s_and_b32 s87, s87, 63
	s_add_u32 s12, s12, 1
	s_cmp_lt_u32 s12, 8
	s_cbranch_scc1 .Lvq_kB
	s_waitcnt vmcnt(0)
	s_add_u32 s32, s62, 16384
	s_addc_u32 s33, s63, 0
	s_add_u32 s34, s62, 20480
	s_addc_u32 s35, s63, 0
	s_add_u32 s36, s62, 24576
	s_addc_u32 s37, s63, 0
	s_add_u32 s38, s62, 28672
	s_addc_u32 s39, s63, 0
	v_pk_add_f32 v[160:161], v[160:161], v[64:65]
	v_pk_add_f32 v[162:163], v[162:163], v[66:67]
	v_pk_add_f32 v[164:165], v[164:165], v[68:69]
	v_pk_add_f32 v[166:167], v[166:167], v[70:71]
	v_pk_add_f32 v[168:169], v[168:169], v[72:73]
	v_pk_add_f32 v[170:171], v[170:171], v[74:75]
	v_pk_add_f32 v[172:173], v[172:173], v[76:77]
	v_pk_add_f32 v[174:175], v[174:175], v[78:79]
	v_pk_mul_f32 v[224:225], v[160:161], v[160:161]
	v_pk_mul_f32 v[226:227], v[162:163], v[162:163]
	v_pk_fma_f32 v[224:225], v[164:165], v[164:165], v[224:225]
	v_pk_fma_f32 v[226:227], v[166:167], v[166:167], v[226:227]
	v_pk_fma_f32 v[224:225], v[168:169], v[168:169], v[224:225]
	v_pk_fma_f32 v[226:227], v[170:171], v[170:171], v[226:227]
	v_pk_fma_f32 v[224:225], v[172:173], v[172:173], v[224:225]
	v_pk_fma_f32 v[226:227], v[174:175], v[174:175], v[226:227]
	v_pk_add_f32 v[224:225], v[224:225], v[226:227]
	s_nop 0
	v_add_f32_e32 v224, v224, v225
	s_nop 1
	v_add_f32_dpp v224, v224, v224 row_ror:8 row_mask:0xf bank_mask:0xf
	s_nop 1
	v_add_f32_dpp v224, v224, v224 row_ror:4 row_mask:0xf bank_mask:0xf
	s_nop 1
	v_add_f32_dpp v224, v224, v224 row_ror:2 row_mask:0xf bank_mask:0xf
	s_nop 1
	v_add_f32_dpp v224, v224, v224 row_ror:1 row_mask:0xf bank_mask:0xf
	s_nop 1
	v_add_f32_dpp v224, v224, v224 row_bcast:15 row_mask:0xa bank_mask:0xf
	s_nop 1
	v_add_f32_dpp v224, v224, v224 row_bcast:31 row_mask:0xc bank_mask:0xf
	s_nop 1
	v_readlane_b32 s15, v224, 63
	s_nop 3
	v_mov_b32_e32 v224, s15
	v_fmamk_f32 v224, v224, 0x3a800000, v248
	v_rsq_f32_e32 v224, v224
	s_nop 1
	v_pk_mul_f32 v[226:227], v[128:129], v[224:225] op_sel_hi:[1,0]
	v_pk_mul_f32 v[160:161], v[160:161], v[226:227]
	v_pk_mul_f32 v[228:229], v[130:131], v[224:225] op_sel_hi:[1,0]
	v_pk_mul_f32 v[162:163], v[162:163], v[228:229]
	v_pk_mul_f32 v[230:231], v[132:133], v[224:225] op_sel_hi:[1,0]
	v_pk_mul_f32 v[164:165], v[164:165], v[230:231]
	v_pk_mul_f32 v[232:233], v[134:135], v[224:225] op_sel_hi:[1,0]
	v_pk_mul_f32 v[166:167], v[166:167], v[232:233]
	v_pk_mul_f32 v[226:227], v[136:137], v[224:225] op_sel_hi:[1,0]
	v_pk_mul_f32 v[168:169], v[168:169], v[226:227]
	v_pk_mul_f32 v[228:229], v[138:139], v[224:225] op_sel_hi:[1,0]
	v_pk_mul_f32 v[170:171], v[170:171], v[228:229]
	v_pk_mul_f32 v[230:231], v[140:141], v[224:225] op_sel_hi:[1,0]
	v_pk_mul_f32 v[172:173], v[172:173], v[230:231]
	v_pk_mul_f32 v[232:233], v[142:143], v[224:225] op_sel_hi:[1,0]
	v_pk_mul_f32 v[174:175], v[174:175], v[232:233]
	v_pk_add_f32 v[176:177], v[176:177], v[80:81]
; DI void peer_item_v(const Params& p, int item) {
;     ...
;     float4 y[4];
;     float ss = 0.f;
; #pragma unroll
;     for (int i = 0; i < 4; ++i) {
;       y[i] = *(const float4*)(orow + 256 * i);
;       y[i].x += out[4 * i]; y[i].y += out[4 * i + 1]; y[i].z += out[4 * i + 2]; y[i].w += out[4 * i + 3];
;       ss += y[i].x * y[i].x + y[i].y * y[i].y + y[i].z * y[i].z + y[i].w * y[i].w;
;     }
;     ss = wave_sum(ss);
;     const float r = rsqrtf(ss * (1.f / 1024.f) + 1e-6f);
; #pragma unroll
;     for (int i = 0; i < 4; ++i) {
;       float4 g = *(const float4*)(p.g_final + 256 * i + lane * 4);
;       y[i].x *= r * g.x; y[i].y *= r * g.y; y[i].z *= r * g.z; y[i].w *= r * g.w;
;       *(float4*)(orow + 256 * i) = y[i];
;     }
	v_pk_add_f32 v[178:179], v[178:179], v[82:83]
	v_pk_add_f32 v[180:181], v[180:181], v[84:85]
	v_pk_add_f32 v[182:183], v[182:183], v[86:87]
	v_pk_add_f32 v[184:185], v[184:185], v[88:89]
	v_pk_add_f32 v[186:187], v[186:187], v[90:91]
	v_pk_add_f32 v[188:189], v[188:189], v[92:93]
	v_pk_add_f32 v[190:191], v[190:191], v[94:95]
	v_pk_mul_f32 v[224:225], v[176:177], v[176:177]
	v_pk_mul_f32 v[226:227], v[178:179], v[178:179]
	v_pk_fma_f32 v[224:225], v[180:181], v[180:181], v[224:225]
	v_pk_fma_f32 v[226:227], v[182:183], v[182:183], v[226:227]
	v_pk_fma_f32 v[224:225], v[184:185], v[184:185], v[224:225]
	v_pk_fma_f32 v[226:227], v[186:187], v[186:187], v[226:227]
	v_pk_fma_f32 v[224:225], v[188:189], v[188:189], v[224:225]
	v_pk_fma_f32 v[226:227], v[190:191], v[190:191], v[226:227]
	v_pk_add_f32 v[224:225], v[224:225], v[226:227]
	s_nop 0
	v_add_f32_e32 v224, v224, v225
	s_nop 1
	v_add_f32_dpp v224, v224, v224 row_ror:8 row_mask:0xf bank_mask:0xf
	s_nop 1
	v_add_f32_dpp v224, v224, v224 row_ror:4 row_mask:0xf bank_mask:0xf
	s_nop 1
	v_add_f32_dpp v224, v224, v224 row_ror:2 row_mask:0xf bank_mask:0xf
	s_nop 1
	v_add_f32_dpp v224, v224, v224 row_ror:1 row_mask:0xf bank_mask:0xf
	s_nop 1
	v_add_f32_dpp v224, v224, v224 row_bcast:15 row_mask:0xa bank_mask:0xf
	s_nop 1
	v_add_f32_dpp v224, v224, v224 row_bcast:31 row_mask:0xc bank_mask:0xf
	s_nop 1
	v_readlane_b32 s15, v224, 63
	s_nop 3
	v_mov_b32_e32 v224, s15
	v_fmamk_f32 v224, v224, 0x3a800000, v248
	v_rsq_f32_e32 v224, v224
	s_nop 1
	v_pk_mul_f32 v[226:227], v[128:129], v[224:225] op_sel_hi:[1,0]
	v_pk_mul_f32 v[176:177], v[176:177], v[226:227]
	v_pk_mul_f32 v[228:229], v[130:131], v[224:225] op_sel_hi:[1,0]
	v_pk_mul_f32 v[178:179], v[178:179], v[228:229]
	v_pk_mul_f32 v[230:231], v[132:133], v[224:225] op_sel_hi:[1,0]
	v_pk_mul_f32 v[180:181], v[180:181], v[230:231]
	v_pk_mul_f32 v[232:233], v[134:135], v[224:225] op_sel_hi:[1,0]
	v_pk_mul_f32 v[182:183], v[182:183], v[232:233]
	v_pk_mul_f32 v[226:227], v[136:137], v[224:225] op_sel_hi:[1,0]
	v_pk_mul_f32 v[184:185], v[184:185], v[226:227]
	v_pk_mul_f32 v[228:229], v[138:139], v[224:225] op_sel_hi:[1,0]
	v_pk_mul_f32 v[186:187], v[186:187], v[228:229]
	v_pk_mul_f32 v[230:231], v[140:141], v[224:225] op_sel_hi:[1,0]
	v_pk_mul_f32 v[188:189], v[188:189], v[230:231]
	v_pk_mul_f32 v[232:233], v[142:143], v[224:225] op_sel_hi:[1,0]
	v_pk_mul_f32 v[190:191], v[190:191], v[232:233]
	v_pk_add_f32 v[192:193], v[192:193], v[96:97]
	v_pk_add_f32 v[194:195], v[194:195], v[98:99]
	v_pk_add_f32 v[196:197], v[196:197], v[100:101]
	v_pk_add_f32 v[198:199], v[198:199], v[102:103]
	v_pk_add_f32 v[200:201], v[200:201], v[104:105]
	v_pk_add_f32 v[202:203], v[202:203], v[106:107]
	v_pk_add_f32 v[204:205], v[204:205], v[108:109]
	v_pk_add_f32 v[206:207], v[206:207], v[110:111]
	v_pk_mul_f32 v[224:225], v[192:193], v[192:193]
	v_pk_mul_f32 v[226:227], v[194:195], v[194:195]
	v_pk_fma_f32 v[224:225], v[196:197], v[196:197], v[224:225]
	v_pk_fma_f32 v[226:227], v[198:199], v[198:199], v[226:227]
	v_pk_fma_f32 v[224:225], v[200:201], v[200:201], v[224:225]
	v_pk_fma_f32 v[226:227], v[202:203], v[202:203], v[226:227]
	v_pk_fma_f32 v[224:225], v[204:205], v[204:205], v[224:225]
	v_pk_fma_f32 v[226:227], v[206:207], v[206:207], v[226:227]
	v_pk_add_f32 v[224:225], v[224:225], v[226:227]
	s_nop 0
	v_add_f32_e32 v224, v224, v225
	s_nop 1
	v_add_f32_dpp v224, v224, v224 row_ror:8 row_mask:0xf bank_mask:0xf
	s_nop 1
	v_add_f32_dpp v224, v224, v224 row_ror:4 row_mask:0xf bank_mask:0xf
	s_nop 1
	v_add_f32_dpp v224, v224, v224 row_ror:2 row_mask:0xf bank_mask:0xf
	s_nop 1
	v_add_f32_dpp v224, v224, v224 row_ror:1 row_mask:0xf bank_mask:0xf
	s_nop 1
	v_add_f32_dpp v224, v224, v224 row_bcast:15 row_mask:0xa bank_mask:0xf
	s_nop 1
	v_add_f32_dpp v224, v224, v224 row_bcast:31 row_mask:0xc bank_mask:0xf
	s_nop 1
	v_readlane_b32 s15, v224, 63
	s_nop 3
	v_mov_b32_e32 v224, s15
	v_fmamk_f32 v224, v224, 0x3a800000, v248
	v_rsq_f32_e32 v224, v224
	s_nop 1
	v_pk_mul_f32 v[226:227], v[128:129], v[224:225] op_sel_hi:[1,0]
	v_pk_mul_f32 v[192:193], v[192:193], v[226:227]
	v_pk_mul_f32 v[228:229], v[130:131], v[224:225] op_sel_hi:[1,0]
	v_pk_mul_f32 v[194:195], v[194:195], v[228:229]
; DI void peer_item_v(const Params& p, int item) {
;     ...
;     float4 y[4];
;     float ss = 0.f;
; #pragma unroll
;     for (int i = 0; i < 4; ++i) {
;       y[i] = *(const float4*)(orow + 256 * i);
;       y[i].x += out[4 * i]; y[i].y += out[4 * i + 1]; y[i].z += out[4 * i + 2]; y[i].w += out[4 * i + 3];
;       ss += y[i].x * y[i].x + y[i].y * y[i].y + y[i].z * y[i].z + y[i].w * y[i].w;
;     }
;     ss = wave_sum(ss);
;     const float r = rsqrtf(ss * (1.f / 1024.f) + 1e-6f);
; #pragma unroll
;     for (int i = 0; i < 4; ++i) {
;       float4 g = *(const float4*)(p.g_final + 256 * i + lane * 4);
;       y[i].x *= r * g.x; y[i].y *= r * g.y; y[i].z *= r * g.z; y[i].w *= r * g.w;
;       *(float4*)(orow + 256 * i) = y[i];
;     }
;   }
; }
	v_pk_mul_f32 v[230:231], v[132:133], v[224:225] op_sel_hi:[1,0]
	v_pk_mul_f32 v[196:197], v[196:197], v[230:231]
	v_pk_mul_f32 v[232:233], v[134:135], v[224:225] op_sel_hi:[1,0]
	v_pk_mul_f32 v[198:199], v[198:199], v[232:233]
	v_pk_mul_f32 v[226:227], v[136:137], v[224:225] op_sel_hi:[1,0]
	v_pk_mul_f32 v[200:201], v[200:201], v[226:227]
	v_pk_mul_f32 v[228:229], v[138:139], v[224:225] op_sel_hi:[1,0]
	v_pk_mul_f32 v[202:203], v[202:203], v[228:229]
	v_pk_mul_f32 v[230:231], v[140:141], v[224:225] op_sel_hi:[1,0]
	v_pk_mul_f32 v[204:205], v[204:205], v[230:231]
	v_pk_mul_f32 v[232:233], v[142:143], v[224:225] op_sel_hi:[1,0]
	v_pk_mul_f32 v[206:207], v[206:207], v[232:233]
	v_pk_add_f32 v[208:209], v[208:209], v[112:113]
	v_pk_add_f32 v[210:211], v[210:211], v[114:115]
	v_pk_add_f32 v[212:213], v[212:213], v[116:117]
	v_pk_add_f32 v[214:215], v[214:215], v[118:119]
	v_pk_add_f32 v[216:217], v[216:217], v[120:121]
	v_pk_add_f32 v[218:219], v[218:219], v[122:123]
	v_pk_add_f32 v[220:221], v[220:221], v[124:125]
	v_pk_add_f32 v[222:223], v[222:223], v[126:127]
	v_pk_mul_f32 v[224:225], v[208:209], v[208:209]
	v_pk_mul_f32 v[226:227], v[210:211], v[210:211]
	v_pk_fma_f32 v[224:225], v[212:213], v[212:213], v[224:225]
	v_pk_fma_f32 v[226:227], v[214:215], v[214:215], v[226:227]
	v_pk_fma_f32 v[224:225], v[216:217], v[216:217], v[224:225]
	v_pk_fma_f32 v[226:227], v[218:219], v[218:219], v[226:227]
	v_pk_fma_f32 v[224:225], v[220:221], v[220:221], v[224:225]
	v_pk_fma_f32 v[226:227], v[222:223], v[222:223], v[226:227]
	v_pk_add_f32 v[224:225], v[224:225], v[226:227]
	s_nop 0
	v_add_f32_e32 v224, v224, v225
	s_nop 1
	v_add_f32_dpp v224, v224, v224 row_ror:8 row_mask:0xf bank_mask:0xf
	s_nop 1
	v_add_f32_dpp v224, v224, v224 row_ror:4 row_mask:0xf bank_mask:0xf
	s_nop 1
	v_add_f32_dpp v224, v224, v224 row_ror:2 row_mask:0xf bank_mask:0xf
	s_nop 1
	v_add_f32_dpp v224, v224, v224 row_ror:1 row_mask:0xf bank_mask:0xf
	s_nop 1
	v_add_f32_dpp v224, v224, v224 row_bcast:15 row_mask:0xa bank_mask:0xf
	s_nop 1
	v_add_f32_dpp v224, v224, v224 row_bcast:31 row_mask:0xc bank_mask:0xf
	s_nop 1
	v_readlane_b32 s15, v224, 63
	s_nop 3
	v_mov_b32_e32 v224, s15
	v_fmamk_f32 v224, v224, 0x3a800000, v248
	v_rsq_f32_e32 v224, v224
	s_nop 1
	v_pk_mul_f32 v[226:227], v[128:129], v[224:225] op_sel_hi:[1,0]
	v_pk_mul_f32 v[208:209], v[208:209], v[226:227]
	v_pk_mul_f32 v[228:229], v[130:131], v[224:225] op_sel_hi:[1,0]
	v_pk_mul_f32 v[210:211], v[210:211], v[228:229]
	v_pk_mul_f32 v[230:231], v[132:133], v[224:225] op_sel_hi:[1,0]
	v_pk_mul_f32 v[212:213], v[212:213], v[230:231]
	v_pk_mul_f32 v[232:233], v[134:135], v[224:225] op_sel_hi:[1,0]
	v_pk_mul_f32 v[214:215], v[214:215], v[232:233]
	v_pk_mul_f32 v[226:227], v[136:137], v[224:225] op_sel_hi:[1,0]
	v_pk_mul_f32 v[216:217], v[216:217], v[226:227]
	v_pk_mul_f32 v[228:229], v[138:139], v[224:225] op_sel_hi:[1,0]
	v_pk_mul_f32 v[218:219], v[218:219], v[228:229]
	v_pk_mul_f32 v[230:231], v[140:141], v[224:225] op_sel_hi:[1,0]
	v_pk_mul_f32 v[220:221], v[220:221], v[230:231]
	v_pk_mul_f32 v[232:233], v[142:143], v[224:225] op_sel_hi:[1,0]
	v_pk_mul_f32 v[222:223], v[222:223], v[232:233]
	global_store_dwordx4 v240, v[160:163], s[32:33]
	global_store_dwordx4 v240, v[164:167], s[32:33] offset:1024
	global_store_dwordx4 v240, v[168:171], s[32:33] offset:2048
	global_store_dwordx4 v240, v[172:175], s[32:33] offset:3072
	global_store_dwordx4 v240, v[176:179], s[34:35]
	global_store_dwordx4 v240, v[180:183], s[34:35] offset:1024
	global_store_dwordx4 v240, v[184:187], s[34:35] offset:2048
	global_store_dwordx4 v240, v[188:191], s[34:35] offset:3072
	global_store_dwordx4 v240, v[192:195], s[36:37]
	global_store_dwordx4 v240, v[196:199], s[36:37] offset:1024
	global_store_dwordx4 v240, v[200:203], s[36:37] offset:2048
	global_store_dwordx4 v240, v[204:207], s[36:37] offset:3072
	global_store_dwordx4 v240, v[208:211], s[38:39]
	global_store_dwordx4 v240, v[212:215], s[38:39] offset:1024
	global_store_dwordx4 v240, v[216:219], s[38:39] offset:2048
	global_store_dwordx4 v240, v[220:223], s[38:39] offset:3072
	s_nop 1
	s_add_i32 s10, s10, s11
	s_cmpk_lt_i32 s10, 0x200
	s_cbranch_scc1 .Lvq_item
